# throttled side-job streaming: 4 instead of 8 cache pieces in flight per thread
# baseline (speedup 1.0000x reference)
; DEVI u32x4 pack8(const f32x4 a, const f32x4 b) { u32x4 w; w.x = cvtpk(a[0], a[1]); w.y = cvtpk(a[2], a[3]); w.z = cvtpk(b[0], b[1]); w.w = cvtpk(b[2], b[3]); return w; }
; DEVI const float* IN(int i) { return *(const float* const __attribute__((address_space(4)))*)(kargs() + 8 * i); }
; DEVI void prologue(int wv, LAS unsigned char* lds) {
;     ...
;     {
;         const float* cache_ckv = IN(2); bf16_t* ckvb = (bf16_t*)(ws + O_CKVB);
;         for (size_t i = gt; i < (size_t)2 * MC * 256 / 8; i += 8 * NGT) {
;             f32x4 a[8], b[8];
; #pragma unroll
;             for (int k = 0; k < 8; ++k) { const size_t ii = i + k * NGT; if (ii < (size_t)2 * MC * 256 / 8) { a[k] = *(const f32x4*)(cache_ckv + ii * 8); b[k] = *(const f32x4*)(cache_ckv + ii * 8 + 4); } }
; #pragma unroll
;             for (int k = 0; k < 8; ++k) { const size_t ii = i + k * NGT; if (ii < (size_t)2 * MC * 256 / 8) *(u32x4*)(ckvb + ii * 8) = pack8(a[k], b[k]); }
;         }
;     }
.Lsjd_loop1_1:
	v_mov_b32_e32 v1, v0
	v_cmp_gt_u32_e64 s[12:13], s10, v1
	v_add_u32_e32 v2, 0xcc00, v0
	v_cmp_gt_u32_e64 s[14:15], s10, v2
	v_add_u32_e32 v3, 0x19800, v0
	v_cmp_gt_u32_e64 s[16:17], s10, v3
	v_add_u32_e32 v4, 0x26400, v0
	v_cmp_gt_u32_e64 s[18:19], s10, v4
	s_mov_b64 exec, s[12:13]
	v_and_b32_e32 v20, 0x3ff, v1
	v_and_b32_e32 v21, 0xfffffc00, v1
	v_lshlrev_b32_e32 v21, 5, v21
	v_and_b32_e32 v22, 31, v20
	v_lshl_or_b32 v21, v22, 10, v21
	v_lshrrev_b32_e32 v22, 8, v20
	v_lshl_or_b32 v21, v22, 8, v21
	v_bfe_u32 v22, v20, 5, 1
	v_lshl_or_b32 v21, v22, 7, v21
	v_bfe_u32 v22, v20, 6, 2
	v_lshl_or_b32 v9, v22, 5, v21
	global_load_dwordx4 v[24:27], v9, s[6:7]
	global_load_dwordx4 v[28:31], v9, s[6:7] offset:16
	s_mov_b64 exec, s[14:15]
	v_and_b32_e32 v20, 0x3ff, v2
	v_and_b32_e32 v21, 0xfffffc00, v2
	v_lshlrev_b32_e32 v21, 5, v21
	v_and_b32_e32 v22, 31, v20
	v_lshl_or_b32 v21, v22, 10, v21
	v_lshrrev_b32_e32 v22, 8, v20
	v_lshl_or_b32 v21, v22, 8, v21
	v_bfe_u32 v22, v20, 5, 1
	v_lshl_or_b32 v21, v22, 7, v21
	v_bfe_u32 v22, v20, 6, 2
	v_lshl_or_b32 v10, v22, 5, v21
	global_load_dwordx4 v[32:35], v10, s[6:7]
	global_load_dwordx4 v[36:39], v10, s[6:7] offset:16
	s_mov_b64 exec, s[16:17]
	v_and_b32_e32 v20, 0x3ff, v3
	v_and_b32_e32 v21, 0xfffffc00, v3
	v_lshlrev_b32_e32 v21, 5, v21
	v_and_b32_e32 v22, 31, v20
	v_lshl_or_b32 v21, v22, 10, v21
	v_lshrrev_b32_e32 v22, 8, v20
	v_lshl_or_b32 v21, v22, 8, v21
	v_bfe_u32 v22, v20, 5, 1
	v_lshl_or_b32 v21, v22, 7, v21
	v_bfe_u32 v22, v20, 6, 2
	v_lshl_or_b32 v11, v22, 5, v21
	global_load_dwordx4 v[40:43], v11, s[6:7]
	global_load_dwordx4 v[44:47], v11, s[6:7] offset:16
	s_mov_b64 exec, s[18:19]
	v_and_b32_e32 v20, 0x3ff, v4
	v_and_b32_e32 v21, 0xfffffc00, v4
	v_lshlrev_b32_e32 v21, 5, v21
	v_and_b32_e32 v22, 31, v20
	v_lshl_or_b32 v21, v22, 10, v21
	v_lshrrev_b32_e32 v22, 8, v20
	v_lshl_or_b32 v21, v22, 8, v21
	v_bfe_u32 v22, v20, 5, 1
	v_lshl_or_b32 v21, v22, 7, v21
	v_bfe_u32 v22, v20, 6, 2
	v_lshl_or_b32 v12, v22, 5, v21
	global_load_dwordx4 v[48:51], v12, s[6:7]
	global_load_dwordx4 v[52:55], v12, s[6:7] offset:16
	s_mov_b64 exec, s[12:13]
	s_waitcnt vmcnt(6)
	v_cvt_pk_bf16_f32 v100, v24, v25
	v_cvt_pk_bf16_f32 v101, v26, v27
	v_cvt_pk_bf16_f32 v102, v28, v29
	v_cvt_pk_bf16_f32 v103, v30, v31
	v_lshlrev_b32_e32 v104, 4, v1
	global_store_dwordx4 v104, v[100:103], s[8:9]
	s_mov_b64 exec, s[14:15]
	s_waitcnt vmcnt(4)
	v_cvt_pk_bf16_f32 v106, v32, v33
	v_cvt_pk_bf16_f32 v107, v34, v35
	v_cvt_pk_bf16_f32 v108, v36, v37
	v_cvt_pk_bf16_f32 v109, v38, v39
	v_lshlrev_b32_e32 v110, 4, v2
	global_store_dwordx4 v110, v[106:109], s[8:9]
	s_mov_b64 exec, s[16:17]
	s_waitcnt vmcnt(2)
	v_cvt_pk_bf16_f32 v100, v40, v41
	v_cvt_pk_bf16_f32 v101, v42, v43
	v_cvt_pk_bf16_f32 v102, v44, v45
	v_cvt_pk_bf16_f32 v103, v46, v47
	v_lshlrev_b32_e32 v104, 4, v3
	global_store_dwordx4 v104, v[100:103], s[8:9]
	s_mov_b64 exec, s[18:19]
	s_waitcnt vmcnt(0)
	v_cvt_pk_bf16_f32 v106, v48, v49
	v_cvt_pk_bf16_f32 v107, v50, v51
	v_cvt_pk_bf16_f32 v108, v52, v53
	v_cvt_pk_bf16_f32 v109, v54, v55
	v_lshlrev_b32_e32 v110, 4, v4
	global_store_dwordx4 v110, v[106:109], s[8:9]
	s_mov_b64 exec, -1
	v_add_u32_e32 v0, 0x33000, v0
	v_cmp_gt_u32_e32 vcc, s10, v0
	s_and_b64 vcc, exec, vcc
	s_cbranch_scc1 .Lsjd_loop1_1

; DEVI u32x4 pack8(const f32x4 a, const f32x4 b) { u32x4 w; w.x = cvtpk(a[0], a[1]); w.y = cvtpk(a[2], a[3]); w.z = cvtpk(b[0], b[1]); w.w = cvtpk(b[2], b[3]); return w; }
; DEVI const float* IN(int i) { return *(const float* const __attribute__((address_space(4)))*)(kargs() + 8 * i); }
; DEVI void prologue(int wv, LAS unsigned char* lds) {
;     ...
;     {
;         const float* cache_ckv = IN(2); bf16_t* ckvb = (bf16_t*)(ws + O_CKVB);
;         for (size_t i = gt; i < (size_t)2 * MC * 256 / 8; i += 8 * NGT) {
;             f32x4 a[8], b[8];
; #pragma unroll
;             for (int k = 0; k < 8; ++k) { const size_t ii = i + k * NGT; if (ii < (size_t)2 * MC * 256 / 8) { a[k] = *(const f32x4*)(cache_ckv + ii * 8); b[k] = *(const f32x4*)(cache_ckv + ii * 8 + 4); } }
; #pragma unroll
;             for (int k = 0; k < 8; ++k) { const size_t ii = i + k * NGT; if (ii < (size_t)2 * MC * 256 / 8) *(u32x4*)(ckvb + ii * 8) = pack8(a[k], b[k]); }
;         }
;     }
.Lsjd_loop4_0:
	v_mov_b32_e32 v1, v0
	v_cmp_gt_u32_e64 s[12:13], s10, v1
	v_add_u32_e32 v2, 0x1f000, v0
	v_cmp_gt_u32_e64 s[14:15], s10, v2
	v_add_u32_e32 v3, 0x3e000, v0
	v_cmp_gt_u32_e64 s[16:17], s10, v3
	v_add_u32_e32 v4, 0x5d000, v0
	v_cmp_gt_u32_e64 s[18:19], s10, v4
	s_mov_b64 exec, s[12:13]
	v_and_b32_e32 v20, 0x3ff, v1
	v_and_b32_e32 v21, 0xfffffc00, v1
	v_lshlrev_b32_e32 v21, 5, v21
	v_and_b32_e32 v22, 31, v20
	v_lshl_or_b32 v21, v22, 10, v21
	v_lshrrev_b32_e32 v22, 8, v20
	v_lshl_or_b32 v21, v22, 8, v21
	v_bfe_u32 v22, v20, 5, 1
	v_lshl_or_b32 v21, v22, 7, v21
	v_bfe_u32 v22, v20, 6, 2
	v_lshl_or_b32 v9, v22, 5, v21
	global_load_dwordx4 v[24:27], v9, s[6:7]
	global_load_dwordx4 v[28:31], v9, s[6:7] offset:16
	s_mov_b64 exec, s[14:15]
	v_and_b32_e32 v20, 0x3ff, v2
	v_and_b32_e32 v21, 0xfffffc00, v2
	v_lshlrev_b32_e32 v21, 5, v21
	v_and_b32_e32 v22, 31, v20
	v_lshl_or_b32 v21, v22, 10, v21
	v_lshrrev_b32_e32 v22, 8, v20
	v_lshl_or_b32 v21, v22, 8, v21
	v_bfe_u32 v22, v20, 5, 1
	v_lshl_or_b32 v21, v22, 7, v21
	v_bfe_u32 v22, v20, 6, 2
	v_lshl_or_b32 v10, v22, 5, v21
	global_load_dwordx4 v[32:35], v10, s[6:7]
	global_load_dwordx4 v[36:39], v10, s[6:7] offset:16
	s_mov_b64 exec, s[16:17]
	v_and_b32_e32 v20, 0x3ff, v3
	v_and_b32_e32 v21, 0xfffffc00, v3
	v_lshlrev_b32_e32 v21, 5, v21
	v_and_b32_e32 v22, 31, v20
	v_lshl_or_b32 v21, v22, 10, v21
	v_lshrrev_b32_e32 v22, 8, v20
	v_lshl_or_b32 v21, v22, 8, v21
	v_bfe_u32 v22, v20, 5, 1
	v_lshl_or_b32 v21, v22, 7, v21
	v_bfe_u32 v22, v20, 6, 2
	v_lshl_or_b32 v11, v22, 5, v21
	global_load_dwordx4 v[40:43], v11, s[6:7]
	global_load_dwordx4 v[44:47], v11, s[6:7] offset:16
	s_mov_b64 exec, s[18:19]
	v_and_b32_e32 v20, 0x3ff, v4
	v_and_b32_e32 v21, 0xfffffc00, v4
	v_lshlrev_b32_e32 v21, 5, v21
	v_and_b32_e32 v22, 31, v20
	v_lshl_or_b32 v21, v22, 10, v21
	v_lshrrev_b32_e32 v22, 8, v20
	v_lshl_or_b32 v21, v22, 8, v21
	v_bfe_u32 v22, v20, 5, 1
	v_lshl_or_b32 v21, v22, 7, v21
	v_bfe_u32 v22, v20, 6, 2
	v_lshl_or_b32 v12, v22, 5, v21
	global_load_dwordx4 v[48:51], v12, s[6:7]
	global_load_dwordx4 v[52:55], v12, s[6:7] offset:16
	s_mov_b64 exec, s[12:13]
	s_waitcnt vmcnt(6)
	v_cvt_pk_bf16_f32 v100, v24, v25
	v_cvt_pk_bf16_f32 v101, v26, v27
	v_cvt_pk_bf16_f32 v102, v28, v29
	v_cvt_pk_bf16_f32 v103, v30, v31
	v_lshlrev_b32_e32 v104, 4, v1
	global_store_dwordx4 v104, v[100:103], s[8:9]
	s_mov_b64 exec, s[14:15]
	s_waitcnt vmcnt(4)
	v_cvt_pk_bf16_f32 v106, v32, v33
	v_cvt_pk_bf16_f32 v107, v34, v35
	v_cvt_pk_bf16_f32 v108, v36, v37
	v_cvt_pk_bf16_f32 v109, v38, v39
	v_lshlrev_b32_e32 v110, 4, v2
	global_store_dwordx4 v110, v[106:109], s[8:9]
	s_mov_b64 exec, s[16:17]
	s_waitcnt vmcnt(2)
	v_cvt_pk_bf16_f32 v100, v40, v41
	v_cvt_pk_bf16_f32 v101, v42, v43
	v_cvt_pk_bf16_f32 v102, v44, v45
	v_cvt_pk_bf16_f32 v103, v46, v47
	v_lshlrev_b32_e32 v104, 4, v3
	global_store_dwordx4 v104, v[100:103], s[8:9]
	s_mov_b64 exec, s[18:19]
	s_waitcnt vmcnt(0)
	v_cvt_pk_bf16_f32 v106, v48, v49
	v_cvt_pk_bf16_f32 v107, v50, v51
	v_cvt_pk_bf16_f32 v108, v52, v53
	v_cvt_pk_bf16_f32 v109, v54, v55
	v_lshlrev_b32_e32 v110, 4, v4
	global_store_dwordx4 v110, v[106:109], s[8:9]
	s_mov_b64 exec, -1
	v_add_u32_e32 v0, 0x7c000, v0
	v_cmp_gt_u32_e32 vcc, s10, v0
	s_and_b64 vcc, exec, vcc
	s_cbranch_scc1 .Lsjd_loop4_0

; DEVI u32x4 pack8(const f32x4 a, const f32x4 b) { u32x4 w; w.x = cvtpk(a[0], a[1]); w.y = cvtpk(a[2], a[3]); w.z = cvtpk(b[0], b[1]); w.w = cvtpk(b[2], b[3]); return w; }
; DEVI const float* IN(int i) { return *(const float* const __attribute__((address_space(4)))*)(kargs() + 8 * i); }
; DEVI void prologue(int wv, LAS unsigned char* lds) {
;     ...
;     {
;         const float* cache_ckv = IN(2); bf16_t* ckvb = (bf16_t*)(ws + O_CKVB);
;         for (size_t i = gt; i < (size_t)2 * MC * 256 / 8; i += 8 * NGT) {
;             f32x4 a[8], b[8];
; #pragma unroll
;             for (int k = 0; k < 8; ++k) { const size_t ii = i + k * NGT; if (ii < (size_t)2 * MC * 256 / 8) { a[k] = *(const f32x4*)(cache_ckv + ii * 8); b[k] = *(const f32x4*)(cache_ckv + ii * 8 + 4); } }
; #pragma unroll
;             for (int k = 0; k < 8; ++k) { const size_t ii = i + k * NGT; if (ii < (size_t)2 * MC * 256 / 8) *(u32x4*)(ckvb + ii * 8) = pack8(a[k], b[k]); }
;         }
;     }
.Lsjd_loop6_0:
	v_mov_b32_e32 v1, v0
	v_cmp_gt_u32_e64 s[12:13], s10, v1
	v_add_u32_e32 v2, 0x1c000, v0
	v_cmp_gt_u32_e64 s[14:15], s10, v2
	v_add_u32_e32 v3, 0x38000, v0
	v_cmp_gt_u32_e64 s[16:17], s10, v3
	v_add_u32_e32 v4, 0x54000, v0
	v_cmp_gt_u32_e64 s[18:19], s10, v4
	s_mov_b64 exec, s[12:13]
	v_and_b32_e32 v20, 0x3ff, v1
	v_and_b32_e32 v21, 0xfffffc00, v1
	v_lshlrev_b32_e32 v21, 5, v21
	v_and_b32_e32 v22, 31, v20
	v_lshl_or_b32 v21, v22, 10, v21
	v_lshrrev_b32_e32 v22, 8, v20
	v_lshl_or_b32 v21, v22, 8, v21
	v_bfe_u32 v22, v20, 5, 1
	v_lshl_or_b32 v21, v22, 7, v21
	v_bfe_u32 v22, v20, 6, 2
	v_lshl_or_b32 v9, v22, 5, v21
	global_load_dwordx4 v[24:27], v9, s[6:7]
	global_load_dwordx4 v[28:31], v9, s[6:7] offset:16
	s_mov_b64 exec, s[14:15]
	v_and_b32_e32 v20, 0x3ff, v2
	v_and_b32_e32 v21, 0xfffffc00, v2
	v_lshlrev_b32_e32 v21, 5, v21
	v_and_b32_e32 v22, 31, v20
	v_lshl_or_b32 v21, v22, 10, v21
	v_lshrrev_b32_e32 v22, 8, v20
	v_lshl_or_b32 v21, v22, 8, v21
	v_bfe_u32 v22, v20, 5, 1
	v_lshl_or_b32 v21, v22, 7, v21
	v_bfe_u32 v22, v20, 6, 2
	v_lshl_or_b32 v10, v22, 5, v21
	global_load_dwordx4 v[32:35], v10, s[6:7]
	global_load_dwordx4 v[36:39], v10, s[6:7] offset:16
	s_mov_b64 exec, s[16:17]
	v_and_b32_e32 v20, 0x3ff, v3
	v_and_b32_e32 v21, 0xfffffc00, v3
	v_lshlrev_b32_e32 v21, 5, v21
	v_and_b32_e32 v22, 31, v20
	v_lshl_or_b32 v21, v22, 10, v21
	v_lshrrev_b32_e32 v22, 8, v20
	v_lshl_or_b32 v21, v22, 8, v21
	v_bfe_u32 v22, v20, 5, 1
	v_lshl_or_b32 v21, v22, 7, v21
	v_bfe_u32 v22, v20, 6, 2
	v_lshl_or_b32 v11, v22, 5, v21
	global_load_dwordx4 v[40:43], v11, s[6:7]
	global_load_dwordx4 v[44:47], v11, s[6:7] offset:16
	s_mov_b64 exec, s[18:19]
	v_and_b32_e32 v20, 0x3ff, v4
	v_and_b32_e32 v21, 0xfffffc00, v4
	v_lshlrev_b32_e32 v21, 5, v21
	v_and_b32_e32 v22, 31, v20
	v_lshl_or_b32 v21, v22, 10, v21
	v_lshrrev_b32_e32 v22, 8, v20
	v_lshl_or_b32 v21, v22, 8, v21
	v_bfe_u32 v22, v20, 5, 1
	v_lshl_or_b32 v21, v22, 7, v21
	v_bfe_u32 v22, v20, 6, 2
	v_lshl_or_b32 v12, v22, 5, v21
	global_load_dwordx4 v[48:51], v12, s[6:7]
	global_load_dwordx4 v[52:55], v12, s[6:7] offset:16
	s_mov_b64 exec, s[12:13]
	s_waitcnt vmcnt(6)
	v_cvt_pk_bf16_f32 v100, v24, v25
	v_cvt_pk_bf16_f32 v101, v26, v27
	v_cvt_pk_bf16_f32 v102, v28, v29
	v_cvt_pk_bf16_f32 v103, v30, v31
	v_lshlrev_b32_e32 v104, 4, v1
	global_store_dwordx4 v104, v[100:103], s[8:9]
	s_mov_b64 exec, s[14:15]
	s_waitcnt vmcnt(4)
	v_cvt_pk_bf16_f32 v106, v32, v33
	v_cvt_pk_bf16_f32 v107, v34, v35
	v_cvt_pk_bf16_f32 v108, v36, v37
	v_cvt_pk_bf16_f32 v109, v38, v39
	v_lshlrev_b32_e32 v110, 4, v2
	global_store_dwordx4 v110, v[106:109], s[8:9]
	s_mov_b64 exec, s[16:17]
	s_waitcnt vmcnt(2)
	v_cvt_pk_bf16_f32 v100, v40, v41
	v_cvt_pk_bf16_f32 v101, v42, v43
	v_cvt_pk_bf16_f32 v102, v44, v45
	v_cvt_pk_bf16_f32 v103, v46, v47
	v_lshlrev_b32_e32 v104, 4, v3
	global_store_dwordx4 v104, v[100:103], s[8:9]
	s_mov_b64 exec, s[18:19]
	s_waitcnt vmcnt(0)
	v_cvt_pk_bf16_f32 v106, v48, v49
	v_cvt_pk_bf16_f32 v107, v50, v51
	v_cvt_pk_bf16_f32 v108, v52, v53
	v_cvt_pk_bf16_f32 v109, v54, v55
	v_lshlrev_b32_e32 v110, 4, v4
	global_store_dwordx4 v110, v[106:109], s[8:9]
	s_mov_b64 exec, -1
	v_add_u32_e32 v0, 0x70000, v0
	v_cmp_gt_u32_e32 vcc, s10, v0
	s_and_b64 vcc, exec, vcc
	s_cbranch_scc1 .Lsjd_loop6_0
